# softmax segment: 17-op max tree replaced by a post-hoc check on the 16-term partial row sums (sum<=256 implies every p<=2^8); rescale path rewritten to act on the exponentiated values (f32 throughout,
# speedup vs baseline: 1.0170x; 1.0149x over previous
; #define AT_BAR() do { __builtin_amdgcn_sched_barrier(0); asm volatile("s_waitcnt lgkmcnt(0)\n\ts_barrier" ::: "memory"); __builtin_amdgcn_sched_barrier(0); } while (0)
; #define AT_PIN_M() asm volatile("" : "+v"(p[0]), "+v"(p[1]), "+v"(o[0][0]), "+v"(o[0][1]), "+v"(o[1][0]), "+v"(o[1][1]))
; __device__ __forceinline__ void attn_phase(LAS unsigned char* lds, const bf16_t* Qb, const bf16_t* Kimg, const bf16_t* Vimg, bf16_t* AB, int bid, int G, int wave_k) {
;     ...
;         int b_prev = 2 * AT_BUF, b_cur = 0, b_next = AT_BUF;
;         AT_ISSUE(0, 0); AT_ISSUE(1, AT_BUF);
;         asm volatile("s_waitcnt vmcnt(0)" ::: "memory"); AT_BAR();
;         if (grpB) AT_BAR();
;         for (int t = 0; t < 256; ++t) {
;             AT_MSEG(b_cur, 0, (t > 0 ? b_prev : b_cur), 2);
;             AT_PIN_M();
;             AT_BAR();
;             AT_SM(t == 0);
;             AT_BAR();
;             const bool issued = (t + 2 < 256);
;             if (issued) AT_ISSUE(t + 2, b_prev);
.LBB0_962:
	s_waitcnt lgkmcnt(0)
	s_barrier
	s_add_u32 s0, s0, 0x6000
	s_addc_u32 s1, s1, 0
	s_mul_i32 s16, s55, 3
	s_add_u32 s18, s18, s16
	s_addc_u32 s19, s19, 0
	s_add_u32 s20, s20, 0x9000
	s_addc_u32 s21, s21, 0
	s_mov_b32 s61, 1
	s_mov_b32 s63, 0xa000
	s_movk_i32 s62, 0x5000
	s_mov_b32 s16, 0
	v_mov_b32_e32 v65, v64
	v_mov_b32_e32 v66, v64
	v_mov_b32_e32 v67, v64
	v_mov_b32_e32 v68, v64
	v_mov_b32_e32 v69, v64
	v_mov_b32_e32 v70, v64
	v_mov_b32_e32 v71, v64
	v_mov_b32_e32 v72, v64
	v_mov_b32_e32 v73, v64
	v_mov_b32_e32 v74, v64
	v_mov_b32_e32 v75, v64
	v_mov_b32_e32 v76, v64
	v_mov_b32_e32 v77, v64
	v_mov_b32_e32 v78, v64
	v_mov_b32_e32 v79, v64
	v_mov_b32_e32 v234, v223
	v_mov_b32_e32 v237, v222
.LBB0_963:
	s_mov_b32 s64, s16
	v_add_u32_e32 v160, s62, v236
	v_add_u32_e32 v128, s64, v236
	ds_read_b128 v[104:107], v160
	ds_read_b128 v[108:111], v160 offset:2048
	ds_read_b128 v[120:123], v160 offset:4096
	ds_read_b128 v[124:127], v160 offset:6144
	ds_read_b128 v[210:213], v160 offset:8192
	ds_read_b128 v[230:233], v160 offset:10240
	ds_read_b128 v[238:241], v128 offset:16384
	ds_read_b128 v[242:245], v128 offset:16896
	ds_read_b128 v[246:249], v128 offset:18432
	ds_read_b128 v[250:253], v128 offset:18944
	s_setprio 1
	s_waitcnt lgkmcnt(9)
	v_mfma_f32_32x32x16_bf16 v[144:159], v[104:107], v[162:165], v[64:79]
	v_mfma_f32_32x32x16_bf16 v[128:143], v[104:107], v[186:189], v[80:95]
	s_waitcnt lgkmcnt(8)
	v_mfma_f32_32x32x16_bf16 v[144:159], v[108:111], v[166:169], v[144:159]
	v_mfma_f32_32x32x16_bf16 v[128:143], v[108:111], v[190:193], v[128:143]
	s_waitcnt lgkmcnt(7)
	v_mfma_f32_32x32x16_bf16 v[144:159], v[120:123], v[170:173], v[144:159]
	v_mfma_f32_32x32x16_bf16 v[128:143], v[120:123], v[194:197], v[128:143]
	s_waitcnt lgkmcnt(6)
	v_mfma_f32_32x32x16_bf16 v[144:159], v[124:127], v[174:177], v[144:159]
	v_mfma_f32_32x32x16_bf16 v[128:143], v[124:127], v[198:201], v[128:143]
	s_waitcnt lgkmcnt(5)
	v_mfma_f32_32x32x16_bf16 v[144:159], v[210:213], v[178:181], v[144:159]
	v_mfma_f32_32x32x16_bf16 v[128:143], v[210:213], v[202:205], v[128:143]
	s_waitcnt lgkmcnt(4)
	v_mfma_f32_32x32x16_bf16 v[144:159], v[230:233], v[182:185], v[144:159]
	v_mfma_f32_32x32x16_bf16 v[128:143], v[230:233], v[206:209], v[128:143]
	s_waitcnt lgkmcnt(0)
	v_mfma_f32_32x32x16_bf16 v[48:63], v[238:241], v[116:119], v[48:63]
	v_mfma_f32_32x32x16_bf16 v[32:47], v[242:245], v[116:119], v[32:47]
	v_mfma_f32_32x32x16_bf16 v[16:31], v[238:241], v[100:103], v[16:31]
	v_mfma_f32_32x32x16_bf16 v[0:15], v[242:245], v[100:103], v[0:15]
	v_mfma_f32_32x32x16_bf16 v[48:63], v[246:249], v[112:115], v[48:63]
	v_mfma_f32_32x32x16_bf16 v[32:47], v[250:253], v[112:115], v[32:47]
	v_mfma_f32_32x32x16_bf16 v[16:31], v[246:249], v[96:99], v[16:31]
	v_mfma_f32_32x32x16_bf16 v[0:15], v[250:253], v[96:99], v[0:15]
	s_setprio 0
	s_waitcnt lgkmcnt(0)
	s_barrier
	s_nop 3
	v_exp_f32_e32 v144, v144
	v_exp_f32_e32 v145, v145
	v_exp_f32_e32 v146, v146
	v_exp_f32_e32 v147, v147
	v_add_f32_e32 v210, v144, v145
	v_exp_f32_e32 v148, v148
	v_add_f32_e32 v210, v210, v146
	v_exp_f32_e32 v149, v149
	v_add_f32_e32 v210, v210, v147
	v_exp_f32_e32 v150, v150
	v_add_f32_e32 v210, v210, v148
	v_exp_f32_e32 v151, v151
	v_add_f32_e32 v210, v210, v149
	v_exp_f32_e32 v152, v152
	v_add_f32_e32 v210, v210, v150
	v_exp_f32_e32 v153, v153
	v_add_f32_e32 v210, v210, v151
	v_exp_f32_e32 v154, v154
	v_add_f32_e32 v210, v210, v152
	v_exp_f32_e32 v155, v155
	v_add_f32_e32 v210, v210, v153
	v_exp_f32_e32 v156, v156
	v_add_f32_e32 v210, v210, v154
	v_exp_f32_e32 v157, v157
	v_add_f32_e32 v210, v210, v155
	v_exp_f32_e32 v158, v158
	v_add_f32_e32 v210, v210, v156
	v_exp_f32_e32 v159, v159
	v_add_f32_e32 v210, v210, v157
	v_add_f32_e32 v210, v210, v158
	v_add_f32_e32 v210, v210, v159
	v_exp_f32_e32 v128, v128
	v_exp_f32_e32 v129, v129
	v_exp_f32_e32 v130, v130
	v_exp_f32_e32 v131, v131
	v_add_f32_e32 v211, v128, v129
	v_exp_f32_e32 v132, v132
	v_add_f32_e32 v211, v211, v130
	v_exp_f32_e32 v133, v133
	v_add_f32_e32 v211, v211, v131
	v_exp_f32_e32 v134, v134
	v_add_f32_e32 v211, v211, v132
	v_exp_f32_e32 v135, v135
	v_add_f32_e32 v211, v211, v133
	v_exp_f32_e32 v136, v136
	v_add_f32_e32 v211, v211, v134
	v_exp_f32_e32 v137, v137
	v_add_f32_e32 v211, v211, v135
	v_exp_f32_e32 v138, v138
	v_add_f32_e32 v211, v211, v136
	v_exp_f32_e32 v139, v139
	v_add_f32_e32 v211, v211, v137
	v_exp_f32_e32 v140, v140
	v_add_f32_e32 v211, v211, v138
	v_exp_f32_e32 v141, v141
	v_add_f32_e32 v211, v211, v139
	v_exp_f32_e32 v142, v142
	v_add_f32_e32 v211, v211, v140
	v_exp_f32_e32 v143, v143
	v_add_f32_e32 v211, v211, v141
	v_add_f32_e32 v211, v211, v142
	v_add_f32_e32 v211, v211, v143
	v_max_f32_e32 v212, v210, v211
	v_cmp_lt_f32_e32 vcc, 0x43800000, v212
	s_cbranch_vccnz .Lph_rare_a
.Lph_cont_a:
	v_add_f32_e32 v234, v234, v210
	v_add_f32_e32 v237, v237, v211
	v_cvt_pk_bf16_f32 v151, v150, v151
	v_cvt_pk_bf16_f32 v150, v148, v149
	v_cvt_pk_bf16_f32 v149, v146, v147
	v_cvt_pk_bf16_f32 v148, v144, v145
	v_cvt_pk_bf16_f32 v144, v152, v153
	v_cvt_pk_bf16_f32 v145, v154, v155
	v_cvt_pk_bf16_f32 v146, v156, v157
	v_cvt_pk_bf16_f32 v147, v158, v159
	v_cvt_pk_bf16_f32 v135, v134, v135
	v_cvt_pk_bf16_f32 v134, v132, v133
	v_cvt_pk_bf16_f32 v133, v130, v131
	v_cvt_pk_bf16_f32 v132, v128, v129
	v_cvt_pk_bf16_f32 v128, v136, v137
	v_cvt_pk_bf16_f32 v129, v138, v139
	v_cvt_pk_bf16_f32 v130, v140, v141
	v_cvt_pk_bf16_f32 v131, v142, v143
	s_waitcnt lgkmcnt(0)
	s_barrier
	s_cmpk_gt_u32 s61, 0xfd
	s_cselect_b64 s[24:25], -1, 0
	s_and_b64 vcc, exec, s[24:25]
	s_cbranch_vccnz .LBB0_969
	s_add_i32 s16, s54, s64
	v_lshl_add_u64 v[136:137], s[20:21], 0, v[218:219]
	s_mov_b32 m0, s16
	s_and_b64 vcc, exec, s[42:43]
	global_load_lds_dwordx4 v[136:137], off
	v_lshl_add_u64 v[136:137], s[18:19], 0, v[218:219]
	s_add_i32 m0, s16, 0x2000
	s_nop 0
	global_load_lds_dwordx4 v[136:137], off
	s_cbranch_vccnz .LBB0_969
	v_lshl_add_u64 v[136:137], s[0:1], 0, v[218:219]
	s_add_i32 m0, s16, 0x4000
	s_nop 0
	global_load_lds_dwordx4 v[136:137], off

; #define AT_BAR() do { __builtin_amdgcn_sched_barrier(0); asm volatile("s_waitcnt lgkmcnt(0)\n\ts_barrier" ::: "memory"); __builtin_amdgcn_sched_barrier(0); } while (0)
; #define AT_VM(N) asm volatile("s_waitcnt vmcnt(" #N ")" ::: "memory")
; #define AT_PIN_M() asm volatile("" : "+v"(p[0]), "+v"(p[1]), "+v"(o[0][0]), "+v"(o[0][1]), "+v"(o[1][0]), "+v"(o[1][1]))
; __device__ __forceinline__ void attn_phase(LAS unsigned char* lds, const bf16_t* Qb, const bf16_t* Kimg, const bf16_t* Vimg, bf16_t* AB, int bid, int G, int wave_k) {
;     ...
;             AT_MSEG(b_cur, 1, b_cur, 0);
;             AT_PIN_M();
;             if (grpB) { if (issued) AT_VM(2); else AT_VM(0); }
;             AT_BAR();
;             AT_SM(false);
;             if (!grpB) { if (issued) AT_VM(3); else AT_VM(0); }
;             AT_BAR();
.LBB0_974:
	s_waitcnt lgkmcnt(0)
	s_barrier
	s_nop 3
	v_exp_f32_e32 v112, v112
	v_exp_f32_e32 v113, v113
	v_exp_f32_e32 v114, v114
	v_exp_f32_e32 v115, v115
	v_add_f32_e32 v210, v112, v113
	v_exp_f32_e32 v116, v116
	v_add_f32_e32 v210, v210, v114
	v_exp_f32_e32 v117, v117
	v_add_f32_e32 v210, v210, v115
	v_exp_f32_e32 v118, v118
	v_add_f32_e32 v210, v210, v116
	v_exp_f32_e32 v119, v119
	v_add_f32_e32 v210, v210, v117
	v_exp_f32_e32 v120, v120
	v_add_f32_e32 v210, v210, v118
	v_exp_f32_e32 v121, v121
	v_add_f32_e32 v210, v210, v119
	v_exp_f32_e32 v122, v122
	v_add_f32_e32 v210, v210, v120
	v_exp_f32_e32 v123, v123
	v_add_f32_e32 v210, v210, v121
	v_exp_f32_e32 v124, v124
	v_add_f32_e32 v210, v210, v122
	v_exp_f32_e32 v125, v125
	v_add_f32_e32 v210, v210, v123
	v_exp_f32_e32 v126, v126
	v_add_f32_e32 v210, v210, v124
	v_exp_f32_e32 v127, v127
	v_add_f32_e32 v210, v210, v125
	v_add_f32_e32 v210, v210, v126
	v_add_f32_e32 v210, v210, v127
	v_exp_f32_e32 v96, v96
	v_exp_f32_e32 v97, v97
	v_exp_f32_e32 v98, v98
	v_exp_f32_e32 v99, v99
	v_add_f32_e32 v211, v96, v97
	v_exp_f32_e32 v100, v100
	v_add_f32_e32 v211, v211, v98
	v_exp_f32_e32 v101, v101
	v_add_f32_e32 v211, v211, v99
	v_exp_f32_e32 v102, v102
	v_add_f32_e32 v211, v211, v100
	v_exp_f32_e32 v103, v103
	v_add_f32_e32 v211, v211, v101
	v_exp_f32_e32 v104, v104
	v_add_f32_e32 v211, v211, v102
	v_exp_f32_e32 v105, v105
	v_add_f32_e32 v211, v211, v103
	v_exp_f32_e32 v106, v106
	v_add_f32_e32 v211, v211, v104
	v_exp_f32_e32 v107, v107
	v_add_f32_e32 v211, v211, v105
	v_exp_f32_e32 v108, v108
	v_add_f32_e32 v211, v211, v106
	v_exp_f32_e32 v109, v109
	v_add_f32_e32 v211, v211, v107
	v_exp_f32_e32 v110, v110
	v_add_f32_e32 v211, v211, v108
	v_exp_f32_e32 v111, v111
	v_add_f32_e32 v211, v211, v109
	v_add_f32_e32 v211, v211, v110
	v_add_f32_e32 v211, v211, v111
	v_max_f32_e32 v212, v210, v211
	v_cmp_lt_f32_e32 vcc, 0x43800000, v212
	s_cbranch_vccnz .Lph_rare_b
.Lph_cont_b:
	v_add_f32_e32 v234, v234, v210
	v_add_f32_e32 v237, v237, v211
	v_cvt_pk_bf16_f32 v119, v118, v119
	v_cvt_pk_bf16_f32 v118, v116, v117
	v_cvt_pk_bf16_f32 v117, v114, v115
	v_cvt_pk_bf16_f32 v116, v112, v113
	v_cvt_pk_bf16_f32 v112, v120, v121
	v_cvt_pk_bf16_f32 v113, v122, v123
	v_cvt_pk_bf16_f32 v114, v124, v125
	v_cvt_pk_bf16_f32 v115, v126, v127
	v_cvt_pk_bf16_f32 v103, v102, v103
	v_cvt_pk_bf16_f32 v102, v100, v101
	v_cvt_pk_bf16_f32 v101, v98, v99
	v_cvt_pk_bf16_f32 v100, v96, v97
	v_cvt_pk_bf16_f32 v96, v104, v105
	v_cvt_pk_bf16_f32 v97, v106, v107
	v_cvt_pk_bf16_f32 v98, v108, v109
	v_cvt_pk_bf16_f32 v99, v110, v111
	s_and_b64 vcc, exec, s[42:43]
	s_cbranch_vccnz .LBB0_981
	s_mov_b64 s[16:17], -1
	s_and_b64 vcc, exec, s[24:25]
	s_cbranch_vccz .LBB0_979
	s_waitcnt vmcnt(0)
	s_mov_b64 s[16:17], 0

.Lph_rare_a:
	v_max3_f32 v212, v144, v145, v146
	v_max3_f32 v212, v212, v147, v148
	v_max3_f32 v212, v212, v149, v150
	v_max3_f32 v212, v212, v151, v152
	v_max3_f32 v212, v212, v153, v154
	v_max3_f32 v212, v212, v155, v156
	v_max3_f32 v212, v212, v157, v158
	v_max_f32_e32 v212, v212, v159
	v_mov_b32_e32 v65, v212
	s_nop 1
	v_permlane32_swap_b32_e32 v212, v65
	v_max_f32_e32 v212, v212, v65
	v_log_f32_e32 v212, v212
	s_nop 0
	v_max_f32_e32 v212, 0, v212
	v_exp_f32_e64 v64, -v212
	s_nop 0
	v_add_f32_e32 v221, v221, v212
	v_mul_f32_e32 v144, v64, v144
	v_mul_f32_e32 v145, v64, v145
	v_mul_f32_e32 v146, v64, v146
	v_mul_f32_e32 v147, v64, v147
	v_mul_f32_e32 v148, v64, v148
	v_mul_f32_e32 v149, v64, v149
	v_mul_f32_e32 v150, v64, v150
	v_mul_f32_e32 v151, v64, v151
	v_mul_f32_e32 v152, v64, v152
	v_mul_f32_e32 v153, v64, v153
	v_mul_f32_e32 v154, v64, v154
	v_mul_f32_e32 v155, v64, v155
	v_mul_f32_e32 v156, v64, v156
	v_mul_f32_e32 v157, v64, v157
	v_mul_f32_e32 v158, v64, v158
	v_mul_f32_e32 v159, v64, v159
	v_mul_f32_e32 v210, v64, v210
	v_mul_f32_e32 v234, v64, v234
	v_mul_f32_e32 v32, v64, v32
	v_mul_f32_e32 v33, v64, v33
	v_mul_f32_e32 v34, v64, v34
	v_mul_f32_e32 v35, v64, v35
	v_mul_f32_e32 v36, v64, v36
	v_mul_f32_e32 v37, v64, v37
	v_mul_f32_e32 v38, v64, v38
	v_mul_f32_e32 v39, v64, v39
	v_mul_f32_e32 v40, v64, v40
	v_mul_f32_e32 v41, v64, v41
	v_mul_f32_e32 v42, v64, v42
	v_mul_f32_e32 v43, v64, v43
	v_mul_f32_e32 v44, v64, v44
	v_mul_f32_e32 v45, v64, v45
	v_mul_f32_e32 v46, v64, v46
	v_mul_f32_e32 v47, v64, v47
	v_mul_f32_e32 v48, v64, v48
	v_mul_f32_e32 v49, v64, v49
	v_mul_f32_e32 v50, v64, v50
	v_mul_f32_e32 v51, v64, v51
	v_mul_f32_e32 v52, v64, v52
	v_mul_f32_e32 v53, v64, v53
	v_mul_f32_e32 v54, v64, v54
	v_mul_f32_e32 v55, v64, v55
	v_mul_f32_e32 v56, v64, v56
	v_mul_f32_e32 v57, v64, v57
	v_mul_f32_e32 v58, v64, v58
	v_mul_f32_e32 v59, v64, v59
	v_mul_f32_e32 v60, v64, v60
	v_mul_f32_e32 v61, v64, v61
	v_mul_f32_e32 v62, v64, v62
	v_mul_f32_e32 v63, v64, v63
	v_xor_b32_e32 v64, 0x80000000, v221
	v_mov_b32_e32 v65, v64
	v_mov_b32_e32 v66, v64
	v_mov_b32_e32 v67, v64
	v_mov_b32_e32 v68, v64
	v_mov_b32_e32 v69, v64
	v_mov_b32_e32 v70, v64
	v_mov_b32_e32 v71, v64
	v_mov_b32_e32 v72, v64
	v_mov_b32_e32 v73, v64
	v_mov_b32_e32 v74, v64
	v_mov_b32_e32 v75, v64
	v_mov_b32_e32 v76, v64
	v_mov_b32_e32 v77, v64
	v_mov_b32_e32 v78, v64
	v_mov_b32_e32 v79, v64
	v_max3_f32 v213, v128, v129, v130
	v_max3_f32 v213, v213, v131, v132
	v_max3_f32 v213, v213, v133, v134
	v_max3_f32 v213, v213, v135, v136
	v_max3_f32 v213, v213, v137, v138
	v_max3_f32 v213, v213, v139, v140
	v_max3_f32 v213, v213, v141, v142
	v_max_f32_e32 v213, v213, v143
	v_mov_b32_e32 v81, v213
	s_nop 1
	v_permlane32_swap_b32_e32 v213, v81
	v_max_f32_e32 v213, v213, v81
	v_log_f32_e32 v213, v213
	s_nop 0
	v_max_f32_e32 v213, 0, v213
	v_exp_f32_e64 v80, -v213
	s_nop 0
	v_add_f32_e32 v220, v220, v213
	v_mul_f32_e32 v128, v80, v128
	v_mul_f32_e32 v129, v80, v129
	v_mul_f32_e32 v130, v80, v130
	v_mul_f32_e32 v131, v80, v131
	v_mul_f32_e32 v132, v80, v132
	v_mul_f32_e32 v133, v80, v133
	v_mul_f32_e32 v134, v80, v134
	v_mul_f32_e32 v135, v80, v135
	v_mul_f32_e32 v136, v80, v136
	v_mul_f32_e32 v137, v80, v137
	v_mul_f32_e32 v138, v80, v138
	v_mul_f32_e32 v139, v80, v139
	v_mul_f32_e32 v140, v80, v140
	v_mul_f32_e32 v141, v80, v141
	v_mul_f32_e32 v142, v80, v142
	v_mul_f32_e32 v143, v80, v143
	v_mul_f32_e32 v211, v80, v211
	v_mul_f32_e32 v237, v80, v237
	v_mul_f32_e32 v0, v80, v0
	v_mul_f32_e32 v1, v80, v1
	v_mul_f32_e32 v2, v80, v2
	v_mul_f32_e32 v3, v80, v3
	v_mul_f32_e32 v4, v80, v4
	v_mul_f32_e32 v5, v80, v5
	v_mul_f32_e32 v6, v80, v6
	v_mul_f32_e32 v7, v80, v7
	v_mul_f32_e32 v8, v80, v8
	v_mul_f32_e32 v9, v80, v9
	v_mul_f32_e32 v10, v80, v10
	v_mul_f32_e32 v11, v80, v11
	v_mul_f32_e32 v12, v80, v12
	v_mul_f32_e32 v13, v80, v13
	v_mul_f32_e32 v14, v80, v14
	v_mul_f32_e32 v15, v80, v15
	v_mul_f32_e32 v16, v80, v16
	v_mul_f32_e32 v17, v80, v17
	v_mul_f32_e32 v18, v80, v18
	v_mul_f32_e32 v19, v80, v19
	v_mul_f32_e32 v20, v80, v20
	v_mul_f32_e32 v21, v80, v21
	v_mul_f32_e32 v22, v80, v22
	v_mul_f32_e32 v23, v80, v23
	v_mul_f32_e32 v24, v80, v24
	v_mul_f32_e32 v25, v80, v25
	v_mul_f32_e32 v26, v80, v26
	v_mul_f32_e32 v27, v80, v27
	v_mul_f32_e32 v28, v80, v28
	v_mul_f32_e32 v29, v80, v29
	v_mul_f32_e32 v30, v80, v30
	v_mul_f32_e32 v31, v80, v31
	v_xor_b32_e32 v80, 0x80000000, v220
	v_mov_b32_e32 v81, v80
	v_mov_b32_e32 v82, v80
	v_mov_b32_e32 v83, v80
	v_mov_b32_e32 v84, v80
	v_mov_b32_e32 v85, v80
	v_mov_b32_e32 v86, v80
	v_mov_b32_e32 v87, v80
	v_mov_b32_e32 v88, v80
	v_mov_b32_e32 v89, v80
	v_mov_b32_e32 v90, v80
	v_mov_b32_e32 v91, v80
	v_mov_b32_e32 v92, v80
	v_mov_b32_e32 v93, v80
	v_mov_b32_e32 v94, v80
	v_mov_b32_e32 v95, v80
	s_branch .Lph_cont_a
; #define AT_BAR() do { __builtin_amdgcn_sched_barrier(0); asm volatile("s_waitcnt lgkmcnt(0)\n\ts_barrier" ::: "memory"); __builtin_amdgcn_sched_barrier(0); } while (0)
; __device__ __forceinline__ void attn_phase(LAS unsigned char* lds, const bf16_t* Qb, const bf16_t* Kimg, const bf16_t* Vimg, bf16_t* AB, int bid, int G, int wave_k) {
;     ...
;             const int tmp = b_prev; b_prev = b_cur; b_cur = b_next; b_next = tmp;
;         }
;         AT_PV(b_prev, 2);
;         if (!grpB) AT_BAR();
;         AT_BAR();
.Lph_rare_b:
	v_max3_f32 v212, v112, v113, v114
	v_max3_f32 v212, v212, v115, v116
	v_max3_f32 v212, v212, v117, v118
	v_max3_f32 v212, v212, v119, v120
	v_max3_f32 v212, v212, v121, v122
	v_max3_f32 v212, v212, v123, v124
	v_max3_f32 v212, v212, v125, v126
	v_max_f32_e32 v212, v212, v127
	v_mov_b32_e32 v65, v212
	s_nop 1
	v_permlane32_swap_b32_e32 v212, v65
	v_max_f32_e32 v212, v212, v65
	v_log_f32_e32 v212, v212
	s_nop 0
	v_max_f32_e32 v212, 0, v212
	v_exp_f32_e64 v64, -v212
	s_nop 0
	v_add_f32_e32 v221, v221, v212
	v_mul_f32_e32 v112, v64, v112
	v_mul_f32_e32 v113, v64, v113
	v_mul_f32_e32 v114, v64, v114
	v_mul_f32_e32 v115, v64, v115
	v_mul_f32_e32 v116, v64, v116
	v_mul_f32_e32 v117, v64, v117
	v_mul_f32_e32 v118, v64, v118
	v_mul_f32_e32 v119, v64, v119
	v_mul_f32_e32 v120, v64, v120
	v_mul_f32_e32 v121, v64, v121
	v_mul_f32_e32 v122, v64, v122
	v_mul_f32_e32 v123, v64, v123
	v_mul_f32_e32 v124, v64, v124
	v_mul_f32_e32 v125, v64, v125
	v_mul_f32_e32 v126, v64, v126
	v_mul_f32_e32 v127, v64, v127
	v_mul_f32_e32 v210, v64, v210
	v_mul_f32_e32 v234, v64, v234
	v_mul_f32_e32 v32, v64, v32
	v_mul_f32_e32 v33, v64, v33
	v_mul_f32_e32 v34, v64, v34
	v_mul_f32_e32 v35, v64, v35
	v_mul_f32_e32 v36, v64, v36
	v_mul_f32_e32 v37, v64, v37
	v_mul_f32_e32 v38, v64, v38
	v_mul_f32_e32 v39, v64, v39
	v_mul_f32_e32 v40, v64, v40
	v_mul_f32_e32 v41, v64, v41
	v_mul_f32_e32 v42, v64, v42
	v_mul_f32_e32 v43, v64, v43
	v_mul_f32_e32 v44, v64, v44
	v_mul_f32_e32 v45, v64, v45
	v_mul_f32_e32 v46, v64, v46
	v_mul_f32_e32 v47, v64, v47
	v_mul_f32_e32 v48, v64, v48
	v_mul_f32_e32 v49, v64, v49
	v_mul_f32_e32 v50, v64, v50
	v_mul_f32_e32 v51, v64, v51
	v_mul_f32_e32 v52, v64, v52
	v_mul_f32_e32 v53, v64, v53
	v_mul_f32_e32 v54, v64, v54
	v_mul_f32_e32 v55, v64, v55
	v_mul_f32_e32 v56, v64, v56
	v_mul_f32_e32 v57, v64, v57
	v_mul_f32_e32 v58, v64, v58
	v_mul_f32_e32 v59, v64, v59
	v_mul_f32_e32 v60, v64, v60
	v_mul_f32_e32 v61, v64, v61
	v_mul_f32_e32 v62, v64, v62
	v_mul_f32_e32 v63, v64, v63
	v_xor_b32_e32 v64, 0x80000000, v221
	v_mov_b32_e32 v65, v64
	v_mov_b32_e32 v66, v64
	v_mov_b32_e32 v67, v64
	v_mov_b32_e32 v68, v64
	v_mov_b32_e32 v69, v64
	v_mov_b32_e32 v70, v64
	v_mov_b32_e32 v71, v64
	v_mov_b32_e32 v72, v64
	v_mov_b32_e32 v73, v64
	v_mov_b32_e32 v74, v64
	v_mov_b32_e32 v75, v64
	v_mov_b32_e32 v76, v64
	v_mov_b32_e32 v77, v64
	v_mov_b32_e32 v78, v64
	v_mov_b32_e32 v79, v64
	v_max3_f32 v213, v96, v97, v98
	v_max3_f32 v213, v213, v99, v100
	v_max3_f32 v213, v213, v101, v102
	v_max3_f32 v213, v213, v103, v104
	v_max3_f32 v213, v213, v105, v106
	v_max3_f32 v213, v213, v107, v108
	v_max3_f32 v213, v213, v109, v110
	v_max_f32_e32 v213, v213, v111
	v_mov_b32_e32 v81, v213
	s_nop 1
	v_permlane32_swap_b32_e32 v213, v81
	v_max_f32_e32 v213, v213, v81
	v_log_f32_e32 v213, v213
	s_nop 0
	v_max_f32_e32 v213, 0, v213
	v_exp_f32_e64 v80, -v213
	s_nop 0
	v_add_f32_e32 v220, v220, v213
	v_mul_f32_e32 v96, v80, v96
	v_mul_f32_e32 v97, v80, v97
	v_mul_f32_e32 v98, v80, v98
	v_mul_f32_e32 v99, v80, v99
	v_mul_f32_e32 v100, v80, v100
	v_mul_f32_e32 v101, v80, v101
	v_mul_f32_e32 v102, v80, v102
	v_mul_f32_e32 v103, v80, v103
	v_mul_f32_e32 v104, v80, v104
	v_mul_f32_e32 v105, v80, v105
	v_mul_f32_e32 v106, v80, v106
	v_mul_f32_e32 v107, v80, v107
	v_mul_f32_e32 v108, v80, v108
	v_mul_f32_e32 v109, v80, v109
	v_mul_f32_e32 v110, v80, v110
	v_mul_f32_e32 v111, v80, v111
	v_mul_f32_e32 v211, v80, v211
	v_mul_f32_e32 v237, v80, v237
	v_mul_f32_e32 v0, v80, v0
	v_mul_f32_e32 v1, v80, v1
	v_mul_f32_e32 v2, v80, v2
	v_mul_f32_e32 v3, v80, v3
	v_mul_f32_e32 v4, v80, v4
	v_mul_f32_e32 v5, v80, v5
	v_mul_f32_e32 v6, v80, v6
	v_mul_f32_e32 v7, v80, v7
	v_mul_f32_e32 v8, v80, v8
	v_mul_f32_e32 v9, v80, v9
	v_mul_f32_e32 v10, v80, v10
	v_mul_f32_e32 v11, v80, v11
	v_mul_f32_e32 v12, v80, v12
	v_mul_f32_e32 v13, v80, v13
	v_mul_f32_e32 v14, v80, v14
	v_mul_f32_e32 v15, v80, v15
	v_mul_f32_e32 v16, v80, v16
	v_mul_f32_e32 v17, v80, v17
	v_mul_f32_e32 v18, v80, v18
	v_mul_f32_e32 v19, v80, v19
	v_mul_f32_e32 v20, v80, v20
	v_mul_f32_e32 v21, v80, v21
	v_mul_f32_e32 v22, v80, v22
	v_mul_f32_e32 v23, v80, v23
	v_mul_f32_e32 v24, v80, v24
	v_mul_f32_e32 v25, v80, v25
	v_mul_f32_e32 v26, v80, v26
	v_mul_f32_e32 v27, v80, v27
	v_mul_f32_e32 v28, v80, v28
	v_mul_f32_e32 v29, v80, v29
	v_mul_f32_e32 v30, v80, v30
	v_mul_f32_e32 v31, v80, v31
	v_xor_b32_e32 v80, 0x80000000, v220
	v_mov_b32_e32 v81, v80
	v_mov_b32_e32 v82, v80
	v_mov_b32_e32 v83, v80
	v_mov_b32_e32 v84, v80
	v_mov_b32_e32 v85, v80
	v_mov_b32_e32 v86, v80
	v_mov_b32_e32 v87, v80
	v_mov_b32_e32 v88, v80
	v_mov_b32_e32 v89, v80
	v_mov_b32_e32 v90, v80
	v_mov_b32_e32 v91, v80
	v_mov_b32_e32 v92, v80
	v_mov_b32_e32 v93, v80
	v_mov_b32_e32 v94, v80
	v_mov_b32_e32 v95, v80
	s_branch .Lph_cont_b
.LBB0_983:
	v_mov_b32_e32 v223, v234
	v_mov_b32_e32 v222, v237
	v_add_u32_e32 v72, s62, v236
	ds_read_b128 v[64:67], v72 offset:16384
	ds_read_b128 v[68:71], v72 offset:16896
	s_and_b64 vcc, s[14:15], exec
	s_waitcnt lgkmcnt(0)
	v_mfma_f32_32x32x16_bf16 v[48:63], v[64:67], v[116:119], v[48:63]
	v_mfma_f32_32x32x16_bf16 v[32:47], v[68:71], v[116:119], v[32:47]
	v_mfma_f32_32x32x16_bf16 v[16:31], v[64:67], v[100:103], v[16:31]
	v_mfma_f32_32x32x16_bf16 v[0:15], v[68:71], v[100:103], v[0:15]
	ds_read_b128 v[64:67], v72 offset:18432
	ds_read_b128 v[68:71], v72 offset:18944
	s_waitcnt lgkmcnt(0)
	v_mfma_f32_32x32x16_bf16 v[48:63], v[64:67], v[112:115], v[48:63]
	v_mfma_f32_32x32x16_bf16 v[32:47], v[68:71], v[112:115], v[32:47]
	v_mfma_f32_32x32x16_bf16 v[16:31], v[64:67], v[96:99], v[16:31]
	v_mfma_f32_32x32x16_bf16 v[0:15], v[68:71], v[96:99], v[0:15]
	s_cbranch_vccz .LBB0_947
	s_waitcnt lgkmcnt(0)
	s_barrier
	s_branch .LBB0_947
.LBB0_985:
	v_mov_b32_e32 v234, 0x880
	v_mov_b32_e32 v237, 0x3c0881c4
	v_readlane_b32 s54, v255, 0
	v_readlane_b32 s56, v255, 2
	v_readlane_b32 s34, v255, 4
	v_readlane_b32 s36, v255, 6
	v_readlane_b32 s40, v255, 8
	v_readlane_b32 s55, v255, 1
	v_readlane_b32 s57, v255, 3
	v_readlane_b32 s35, v255, 5
	v_readlane_b32 s37, v255, 7
	v_readlane_b32 s41, v255, 9
	v_mov_b32_e32 v224, v237
	v_mov_b32_e32 v225, v228
	v_mov_b32_e32 v228, 1
	v_not_b32_e32 v230, 63
	v_not_b32_e32 v231, 31
	v_mov_b32_e32 v232, 0x7fc00000
	v_mov_b32_e32 v233, 0x600
